# add: sample-scan trips prefetch the operand loads of steps 1-3 at the top of the trip (both code copies)
# speedup vs baseline: 1.0062x; 1.0062x over previous
.LBB0_744:
	s_add_i32 s18, s23, s24
	s_ashr_i32 s30, s18, 8
	s_lshl_b32 s10, s30, 10
	s_and_b32 s29, s26, 0x3c0
	v_readlane_b32 s36, v245, 6
	s_or_b32 s31, s29, s10
	s_mul_i32 s11, s30, 0x3480
	v_readlane_b32 s40, v245, 10
	s_mul_hi_i32 s10, s30, 0x3480
	v_readlane_b32 s41, v245, 11
	s_add_u32 s14, s40, s11
	s_addc_u32 s15, s41, s10
	s_add_i32 s19, s25, s24
	s_cmp_lt_i32 s19, 0x8000
	s_cselect_b64 s[10:11], -1, 0
	s_cmpk_gt_i32 s19, 0x7fff
	s_cselect_b64 s[12:13], -1, 0
	s_and_b64 s[16:17], s[12:13], exec
	v_readlane_b32 s37, v245, 7
	s_cselect_b32 s16, s18, s19
	s_ashr_i32 s36, s16, 8
	s_lshl_b32 s37, s16, 2
	v_readlane_b32 s38, v245, 8
	s_lshl_b32 s16, s36, 10
	s_and_b32 s28, s37, 0x3c0
	s_or_b32 s38, s28, s16
	s_mul_i32 s17, s36, 0x3480
	s_mul_hi_i32 s16, s36, 0x3480
	s_add_u32 s18, s40, s17
	s_addc_u32 s19, s41, s16
	s_lshl_b32 s30, s30, 2
	s_add_i32 s16, s30, 0x2040
	s_ashr_i32 s17, s16, 31
	s_lshl_b64 s[34:35], s[16:17], 10
	s_or_b32 s34, s34, s29
	v_mov_b32_e32 v5, s35
	v_or_b32_e32 v4, s34, v16
	v_lshl_add_u64 v[0:1], v[4:5], 3, s[8:9]
	v_and_or_b32 v30, s26, 60, v17
	global_load_dwordx4 v[34:37], v[0:1], off
	global_load_dwordx4 v[40:43], v[0:1], off offset:16
	v_or_b32_e32 v0, s31, v30
	v_ashrrev_i32_e32 v1, 31, v0
	v_readlane_b32 s42, v245, 12
	v_readlane_b32 s43, v245, 13
	v_readlane_b32 s44, v245, 14
	v_readlane_b32 s45, v245, 15
	v_readlane_b32 s46, v245, 16
	v_readlane_b32 s47, v245, 17
	v_readlane_b32 s48, v245, 18
	v_readlane_b32 s49, v245, 19
	v_readlane_b32 s50, v245, 20
	v_readlane_b32 s51, v245, 21
	v_lshlrev_b64 v[22:23], 8, v[0:1]
	v_or_b32_e32 v0, s29, v30
	v_or_b32_e32 v0, 0x800, v0
	s_mul_i32 s34, s16, 0x3480
	v_readlane_b32 s40, v245, 22
	v_lshlrev_b32_e32 v28, 2, v0
	s_mul_hi_i32 s31, s16, 0x3480
	s_add_u32 s34, s2, s34
	v_readlane_b32 s41, v245, 23
	s_addc_u32 s35, s3, s31
	s_nop 3
	global_load_dword v27, v28, s[40:41]
	global_load_dword v39, v28, s[14:15]
	global_load_dword v33, v28, s[34:35]
	s_lshl_b32 s31, s36, 2
	s_add_i32 s14, s31, 0x2040
	v_lshl_add_u64 v[0:1], v[18:19], 0, v[22:23]
	v_and_or_b32 v31, s37, 60, v17
	s_ashr_i32 s15, s14, 31
	global_load_dwordx4 v[44:47], v[0:1], off
	v_or_b32_e32 v0, s38, v31
	s_lshl_b64 s[34:35], s[14:15], 10
	v_ashrrev_i32_e32 v1, 31, v0
	v_or_b32_e32 v6, s28, v31
	v_lshl_add_u64 v[4:5], v[4:5], 2, s[0:1]
	s_or_b32 s34, s34, s28
	v_lshlrev_b64 v[24:25], 8, v[0:1]
	v_or_b32_e32 v6, 0x800, v6
	global_load_dwordx4 v[48:51], v[4:5], off
	v_mov_b32_e32 v5, s35
	v_or_b32_e32 v4, s34, v16
	s_mul_i32 s34, s14, 0x3480
	v_lshl_add_u64 v[0:1], v[18:19], 0, v[24:25]
	v_lshlrev_b32_e32 v29, 2, v6
	v_lshl_add_u64 v[6:7], v[4:5], 2, s[0:1]
	v_lshl_add_u64 v[12:13], v[4:5], 3, s[8:9]
	s_mul_hi_i32 s35, s14, 0x3480
	s_add_u32 s34, s2, s34
	global_load_dwordx4 v[0:3], v[0:1], off
	s_nop 0
	global_load_dwordx4 v[8:11], v[12:13], off offset:16
	s_nop 0
	global_load_dwordx4 v[4:7], v[6:7], off
	s_nop 0
	global_load_dwordx4 v[12:15], v[12:13], off
	s_addc_u32 s35, s3, s35
	global_load_dword v26, v29, s[40:41]
	global_load_dword v38, v29, s[18:19]
	global_load_dword v32, v29, s[34:35]
	s_add_i32 s64, s30, 0x2041
	s_ashr_i32 s65, s64, 31
	s_lshl_b64 s[66:67], s[64:65], 10
	v_mov_b32_e32 v236, s29
	v_or3_b32 v236, s66, v236, v16
	v_or3_b32 v237, s67, 0, 0
	s_mul_hi_i32 s67, s64, 0x3480
	s_mul_i32 s66, s64, 0x3480
	s_add_u32 s66, s2, s66
	s_addc_u32 s67, s3, s67
	v_lshl_add_u64 v[238:239], v[236:237], 3, s[8:9]
	global_load_dwordx4 v[148:151], v[238:239], off
	global_load_dwordx4 v[152:155], v[238:239], off offset:16
	global_load_dword v172, v28, s[66:67]
	v_lshl_add_u64 v[238:239], v[236:237], 2, s[0:1]
	global_load_dwordx4 v[156:159], v[238:239], off
	s_add_i32 s64, s31, 0x2041
	s_ashr_i32 s65, s64, 31
	s_lshl_b64 s[66:67], s[64:65], 10
	v_mov_b32_e32 v236, s28
	v_or3_b32 v236, s66, v236, v16
	v_or3_b32 v237, s67, 0, 0
	s_mul_hi_i32 s67, s64, 0x3480
	s_mul_i32 s66, s64, 0x3480
	s_add_u32 s66, s2, s66
	s_addc_u32 s67, s3, s67
	v_lshl_add_u64 v[238:239], v[236:237], 3, s[8:9]
	global_load_dwordx4 v[160:163], v[238:239], off
	global_load_dwordx4 v[164:167], v[238:239], off offset:16
	global_load_dword v173, v29, s[66:67]
	v_lshl_add_u64 v[238:239], v[236:237], 2, s[0:1]
	global_load_dwordx4 v[168:171], v[238:239], off
	s_add_i32 s64, s30, 0x2042
	s_ashr_i32 s65, s64, 31
	s_lshl_b64 s[66:67], s[64:65], 10
	v_mov_b32_e32 v236, s29
	v_or3_b32 v236, s66, v236, v16
	v_or3_b32 v237, s67, 0, 0
	s_mul_hi_i32 s67, s64, 0x3480
	s_mul_i32 s66, s64, 0x3480
	s_add_u32 s66, s2, s66
	s_addc_u32 s67, s3, s67
	v_lshl_add_u64 v[238:239], v[236:237], 3, s[8:9]
	global_load_dwordx4 v[180:183], v[238:239], off
	global_load_dwordx4 v[184:187], v[238:239], off offset:16
	global_load_dword v204, v28, s[66:67]
	v_lshl_add_u64 v[238:239], v[236:237], 2, s[0:1]
	global_load_dwordx4 v[188:191], v[238:239], off
	s_add_i32 s64, s31, 0x2042
	s_ashr_i32 s65, s64, 31
	s_lshl_b64 s[66:67], s[64:65], 10
	v_mov_b32_e32 v236, s28
	v_or3_b32 v236, s66, v236, v16
	v_or3_b32 v237, s67, 0, 0
	s_mul_hi_i32 s67, s64, 0x3480
	s_mul_i32 s66, s64, 0x3480
	s_add_u32 s66, s2, s66
	s_addc_u32 s67, s3, s67
	v_lshl_add_u64 v[238:239], v[236:237], 3, s[8:9]
	global_load_dwordx4 v[192:195], v[238:239], off
	global_load_dwordx4 v[196:199], v[238:239], off offset:16
	global_load_dword v205, v29, s[66:67]
	v_lshl_add_u64 v[238:239], v[236:237], 2, s[0:1]
	global_load_dwordx4 v[200:203], v[238:239], off
	s_add_i32 s64, s30, 0x2043
	s_ashr_i32 s65, s64, 31
	s_lshl_b64 s[66:67], s[64:65], 10
	v_mov_b32_e32 v236, s29
	v_or3_b32 v236, s66, v236, v16
	v_or3_b32 v237, s67, 0, 0
	s_mul_hi_i32 s67, s64, 0x3480
	s_mul_i32 s66, s64, 0x3480
	s_add_u32 s66, s2, s66
	s_addc_u32 s67, s3, s67
	v_lshl_add_u64 v[238:239], v[236:237], 3, s[8:9]
	global_load_dwordx4 v[210:213], v[238:239], off
	global_load_dwordx4 v[214:217], v[238:239], off offset:16
	global_load_dword v234, v28, s[66:67]
	v_lshl_add_u64 v[238:239], v[236:237], 2, s[0:1]
	global_load_dwordx4 v[218:221], v[238:239], off
	s_add_i32 s64, s31, 0x2043
	s_ashr_i32 s65, s64, 31
	s_lshl_b64 s[66:67], s[64:65], 10
	v_mov_b32_e32 v236, s28
	v_or3_b32 v236, s66, v236, v16
	v_or3_b32 v237, s67, 0, 0
	s_mul_hi_i32 s67, s64, 0x3480
	s_mul_i32 s66, s64, 0x3480
	s_add_u32 s66, s2, s66
	s_addc_u32 s67, s3, s67
	v_lshl_add_u64 v[238:239], v[236:237], 3, s[8:9]
	global_load_dwordx4 v[222:225], v[238:239], off
	global_load_dwordx4 v[226:229], v[238:239], off offset:16
	global_load_dword v235, v29, s[66:67]
	v_lshl_add_u64 v[238:239], v[236:237], 2, s[0:1]
	global_load_dwordx4 v[230:233], v[238:239], off
	v_lshlrev_b32_e32 v30, 2, v30
	v_readlane_b32 s39, v245, 9
	v_readlane_b32 s42, v245, 24
	v_readlane_b32 s43, v245, 25
	v_readlane_b32 s44, v245, 26
	v_readlane_b32 s45, v245, 27
	v_readlane_b32 s46, v245, 28
	v_readlane_b32 s47, v245, 29
	v_readlane_b32 s48, v245, 30
	v_readlane_b32 s49, v245, 31
	v_readlane_b32 s50, v245, 32
	v_readlane_b32 s51, v245, 33
	v_readlane_b32 s52, v245, 34
	v_readlane_b32 s53, v245, 35
	v_readlane_b32 s54, v245, 36
	v_readlane_b32 s55, v245, 37
	s_waitcnt vmcnt(37)
	v_lshlrev_b32_e32 v56, 16, v35
	s_waitcnt vmcnt(32)
	v_mul_f32 v56, v44, v56
	v_lshlrev_b32_e32 v57, 16, v37
	v_lshlrev_b32_e32 v58, 16, v41
	v_fma_f32 v56, v45, v57, v56
	v_lshlrev_b32_e32 v59, 16, v43
	v_mul_f32 v58, v46, v58
	v_lshlrev_b32_e32 v52, 16, v34
	v_fma_f32 v57, v47, v59, v58
	v_lshlrev_b32_e32 v53, 16, v36
	v_add_f32 v56, v56, v57
	v_and_b32_e32 v34, 0xffff0000, v34
	v_and_b32_e32 v36, 0xffff0000, v36
	v_add_f32_dpp v56, v56, v56 row_ror:8 row_mask:0xf bank_mask:0xf bound_ctrl:1
	v_and_b32_e32 v35, 0xffff0000, v35
	v_lshlrev_b32_e32 v54, 16, v40
	v_add_f32_dpp v56, v56, v56 row_ror:4 row_mask:0xf bank_mask:0xf bound_ctrl:1
	v_and_b32_e32 v40, 0xffff0000, v40
	v_and_b32_e32 v37, 0xffff0000, v37
	v_add_f32_dpp v56, v56, v56 row_ror:2 row_mask:0xf bank_mask:0xf bound_ctrl:1
	v_lshlrev_b32_e32 v55, 16, v42
	v_and_b32_e32 v42, 0xffff0000, v42
	v_add_f32_dpp v56, v56, v56 row_ror:1 row_mask:0xf bank_mask:0xf bound_ctrl:1
	v_and_b32_e32 v41, 0xffff0000, v41
	v_sub_f32_e32 v39, v39, v33
	v_fma_f32 v39, v27, v39, v33
	v_mul_f32 v34, v39, v34
	v_mul_f32 v36, v39, v36
	v_and_b32_e32 v43, 0xffff0000, v43
	v_fma_f32 v34, v56, v35, v34
	v_fma_f32 v35, v56, v37, v36
	v_mul_f32 v36, v39, v40
	v_mul_f32 v37, v39, v42
	s_waitcnt vmcnt(31)
	v_fma_f32 v34, v44, v48, v34
	v_fma_f32 v36, v56, v41, v36
	v_fma_f32 v35, v45, v49, v35
	v_fma_f32 v37, v56, v43, v37
	s_nop 0
	v_mul_f32 v39, v34, v52
	v_fma_f32 v36, v46, v50, v36
	v_fma_f32 v37, v47, v51, v37
	s_nop 0
	v_fma_f32 v39, v35, v53, v39
	v_mul_f32 v40, v36, v54
	s_nop 0
	v_fma_f32 v40, v37, v55, v40
	s_nop 0
	v_add_f32 v39, v39, v40
	v_mov_b32_e32 v40, 0
	s_nop 0
	v_add_f32_dpp v39, v39, v39 row_ror:8 row_mask:0xf bank_mask:0xf bound_ctrl:1
	s_nop 1
	v_add_f32_dpp v39, v39, v39 row_ror:4 row_mask:0xf bank_mask:0xf bound_ctrl:1
	s_nop 1
	v_add_f32_dpp v39, v39, v39 row_ror:2 row_mask:0xf bank_mask:0xf bound_ctrl:1
	s_nop 1
	v_mov_b32_dpp v40, v39 row_ror:1 row_mask:0xf bank_mask:0xf
	s_and_saveexec_b64 s[18:19], s[6:7]
	s_cbranch_execz .LBB0_746
	s_lshl_b64 s[16:17], s[16:17], 12
	s_add_u32 s16, s20, s16
	s_addc_u32 s17, s21, s17
	s_lshl_b32 s34, s29, 2
	s_add_u32 s16, s16, s34
	s_addc_u32 s17, s17, 0
	v_add_f32_e32 v39, v39, v40
	global_store_dword v30, v39, s[16:17]
.LBB0_746:
	s_or_b64 exec, exec, s[18:19]
	s_waitcnt vmcnt(27)
	v_lshlrev_b32_e32 v41, 16, v14
	v_and_b32_e32 v39, 0xffff0000, v14
	v_lshlrev_b32_e32 v14, 16, v13
	s_waitcnt vmcnt(24)
	v_sub_f32_e32 v38, v38, v32
	v_mul_f32 v14, v0, v14
	v_lshlrev_b32_e32 v44, 16, v15
	v_lshlrev_b32_e32 v45, 16, v9
	v_fma_f32 v47, v26, v38, v32
	v_fma_f32 v14, v1, v44, v14
	v_mul_f32 v38, v2, v45
	v_lshlrev_b32_e32 v46, 16, v11
	v_fma_f32 v38, v3, v46, v38
	v_lshlrev_b32_e32 v40, 16, v12
	v_add_f32 v14, v14, v38
	v_and_b32_e32 v12, 0xffff0000, v12
	v_mul_f32 v12, v47, v12
	v_and_b32_e32 v13, 0xffff0000, v13
	v_add_f32_dpp v14, v14, v14 row_ror:8 row_mask:0xf bank_mask:0xf bound_ctrl:1
	v_and_b32_e32 v15, 0xffff0000, v15
	v_lshlrev_b32_e32 v42, 16, v8
	v_add_f32_dpp v14, v14, v14 row_ror:4 row_mask:0xf bank_mask:0xf bound_ctrl:1
	v_and_b32_e32 v8, 0xffff0000, v8
	v_and_b32_e32 v9, 0xffff0000, v9
	v_add_f32_dpp v14, v14, v14 row_ror:2 row_mask:0xf bank_mask:0xf bound_ctrl:1
	v_lshlrev_b32_e32 v43, 16, v10
	v_and_b32_e32 v10, 0xffff0000, v10
	v_add_f32_dpp v44, v14, v14 row_ror:1 row_mask:0xf bank_mask:0xf bound_ctrl:1
	v_fma_f32 v12, v44, v13, v12
	v_and_b32_e32 v11, 0xffff0000, v11
	v_fma_f32 v14, v0, v4, v12
	v_mul_f32 v0, v47, v39
	s_nor_b64 s[12:13], s[4:5], s[12:13]
	v_fma_f32 v0, v44, v15, v0
	v_lshlrev_b32_e32 v31, 2, v31
	v_fma_f32 v15, v1, v5, v0
	v_mul_f32 v0, v47, v8
	s_nop 0
	v_fma_f32 v0, v44, v9, v0
	s_nop 0
	v_fma_f32 v38, v2, v6, v0
	v_mul_f32 v0, v47, v10
	s_nop 0
	v_fma_f32 v0, v44, v11, v0
	v_mul_f32 v1, v38, v42
	s_nop 0
	v_fma_f32 v39, v3, v7, v0
	v_mul_f32 v0, v14, v40
	s_nop 0
	v_fma_f32 v0, v15, v41, v0
	v_fma_f32 v1, v39, v43, v1
	s_nop 0
	v_add_f32 v0, v0, v1
	v_mov_b32_e32 v1, 0
	s_nop 0
	v_add_f32_dpp v0, v0, v0 row_ror:8 row_mask:0xf bank_mask:0xf bound_ctrl:1
	s_nop 1
	v_add_f32_dpp v0, v0, v0 row_ror:4 row_mask:0xf bank_mask:0xf bound_ctrl:1
	s_nop 1
	v_add_f32_dpp v0, v0, v0 row_ror:2 row_mask:0xf bank_mask:0xf bound_ctrl:1
	s_nop 1
	v_mov_b32_dpp v1, v0 row_ror:1 row_mask:0xf bank_mask:0xf
	s_and_saveexec_b64 s[16:17], s[12:13]
	s_cbranch_execz .LBB0_748
	s_lshl_b64 s[14:15], s[14:15], 12
	s_add_u32 s14, s20, s14
	s_addc_u32 s15, s21, s15
	s_lshl_b32 s18, s28, 2
	s_add_u32 s14, s14, s18
	s_addc_u32 s15, s15, 0
	v_add_f32_e32 v0, v0, v1
	global_store_dword v31, v0, s[14:15]
.LBB0_748:
	s_or_b64 exec, exec, s[16:17]
	s_add_i32 s16, s30, 0x2041
	s_ashr_i32 s17, s16, 31
	s_lshl_b64 s[14:15], s[16:17], 10
	v_mov_b32_e32 v0, s29
	v_or3_b32 v0, s14, v0, v16
	s_mul_i32 s14, s16, 0x3480
	v_or3_b32 v1, s15, 0, 0
	s_mul_hi_i32 s15, s16, 0x3480
	s_add_u32 s14, s2, s14
	v_lshl_add_u64 v[2:3], v[0:1], 3, s[8:9]
	s_addc_u32 s15, s3, s15
	s_waitcnt vmcnt(16)
	v_mov_b64_e32 v[40:41], v[148:149]
	v_mov_b64_e32 v[42:43], v[150:151]
	v_mov_b64_e32 v[44:45], v[152:153]
	v_mov_b64_e32 v[46:47], v[154:155]
	v_mov_b32_e32 v13, v172
	v_lshl_add_u64 v[0:1], v[0:1], 2, s[0:1]
	v_mov_b64_e32 v[48:49], v[156:157]
	v_mov_b64_e32 v[50:51], v[158:159]
	s_add_i32 s14, s31, 0x2041
	s_ashr_i32 s15, s14, 31
	v_mov_b32_e32 v2, s28
	s_lshl_b64 s[18:19], s[14:15], 10
	s_mul_i32 s35, s14, 0x3480
	v_or3_b32 v1, s19, 0, 0
	v_or3_b32 v0, s18, v2, v16
	s_mul_hi_i32 s34, s14, 0x3480
	s_add_u32 s18, s2, s35
	v_lshl_add_u64 v[2:3], v[0:1], 2, s[0:1]
	v_lshl_add_u64 v[8:9], v[0:1], 3, s[8:9]
	s_addc_u32 s19, s3, s34
	v_mov_b64_e32 v[4:5], v[164:165]
	v_mov_b64_e32 v[6:7], v[166:167]
	s_nop 0
	v_mov_b64_e32 v[0:1], v[168:169]
	v_mov_b64_e32 v[2:3], v[170:171]
	s_nop 0
	v_mov_b64_e32 v[8:9], v[160:161]
	v_mov_b64_e32 v[10:11], v[162:163]
	s_nop 0
	v_mov_b32_e32 v12, v173
	s_waitcnt vmcnt(23)
	v_lshlrev_b32_e32 v56, 16, v41
	v_lshlrev_b32_e32 v52, 16, v40
	s_waitcnt vmcnt(21)
	v_sub_f32_e32 v33, v33, v13
	v_lshlrev_b32_e32 v53, 16, v42
	v_lshlrev_b32_e32 v54, 16, v44
	v_lshlrev_b32_e32 v55, 16, v46
	v_and_b32_e32 v40, 0xffff0000, v40
	v_and_b32_e32 v42, 0xffff0000, v42
	v_and_b32_e32 v44, 0xffff0000, v44
	v_and_b32_e32 v46, 0xffff0000, v46
	v_lshlrev_b32_e32 v57, 16, v43
	v_lshlrev_b32_e32 v58, 16, v45
	v_fma_f32 v33, v27, v33, v13
	v_mul_f32 v56, v34, v56
	v_lshlrev_b32_e32 v59, 16, v47
	v_mul_f32 v58, v36, v58
	v_fma_f32 v56, v35, v57, v56
	v_mul_f32 v40, v33, v40
	v_mul_f32 v42, v33, v42
	v_mul_f32 v44, v33, v44
	v_mul_f32 v33, v33, v46
	s_nop 0
	v_fma_f32 v57, v37, v59, v58
	v_and_b32_e32 v47, 0xffff0000, v47
	v_add_f32 v46, v56, v57
	v_and_b32_e32 v41, 0xffff0000, v41
	v_and_b32_e32 v43, 0xffff0000, v43
	v_add_f32_dpp v46, v46, v46 row_ror:8 row_mask:0xf bank_mask:0xf bound_ctrl:1
	v_and_b32_e32 v45, 0xffff0000, v45
	s_nop 0
	v_add_f32_dpp v46, v46, v46 row_ror:4 row_mask:0xf bank_mask:0xf bound_ctrl:1
	s_nop 1
	v_add_f32_dpp v46, v46, v46 row_ror:2 row_mask:0xf bank_mask:0xf bound_ctrl:1
	s_nop 1
	v_add_f32_dpp v46, v46, v46 row_ror:1 row_mask:0xf bank_mask:0xf bound_ctrl:1
	v_fma_f32 v33, v46, v47, v33
	v_fma_f32 v40, v46, v41, v40
	v_fma_f32 v41, v46, v43, v42
	v_fma_f32 v42, v46, v45, v44
	s_waitcnt vmcnt(20)
	v_fma_f32 v34, v34, v48, v40
	v_fma_f32 v37, v37, v51, v33
	v_fma_f32 v35, v35, v49, v41
	v_fma_f32 v36, v36, v50, v42
	s_nop 0
	v_mul_f32 v33, v34, v52
	v_mul_f32 v40, v36, v54
	s_nop 0
	v_fma_f32 v33, v35, v53, v33
	v_fma_f32 v40, v37, v55, v40
	s_nop 0
	v_add_f32 v33, v33, v40
	v_mov_b32_e32 v40, 0
	s_nop 0
	v_add_f32_dpp v33, v33, v33 row_ror:8 row_mask:0xf bank_mask:0xf bound_ctrl:1
	s_nop 1
	v_add_f32_dpp v33, v33, v33 row_ror:4 row_mask:0xf bank_mask:0xf bound_ctrl:1
	s_nop 1
	v_add_f32_dpp v33, v33, v33 row_ror:2 row_mask:0xf bank_mask:0xf bound_ctrl:1
	s_nop 1
	v_mov_b32_dpp v40, v33 row_ror:1 row_mask:0xf bank_mask:0xf
	s_and_saveexec_b64 s[18:19], s[6:7]
	s_cbranch_execz .LBB0_750
	s_lshl_b64 s[16:17], s[16:17], 12
	s_add_u32 s16, s20, s16
	s_addc_u32 s17, s21, s17
	s_lshl_b32 s34, s29, 2
	s_add_u32 s16, s16, s34
	s_addc_u32 s17, s17, 0
	v_add_f32_e32 v33, v33, v40
	global_store_dword v30, v33, s[16:17]
.LBB0_750:
	s_or_b64 exec, exec, s[18:19]
	s_waitcnt vmcnt(17)
	v_lshlrev_b32_e32 v42, 16, v9
	v_lshlrev_b32_e32 v43, 16, v11
	v_mul_f32 v42, v14, v42
	v_lshlrev_b32_e32 v45, 16, v5
	v_fma_f32 v42, v15, v43, v42
	v_mul_f32 v43, v38, v45
	v_lshlrev_b32_e32 v46, 16, v7
	v_fma_f32 v43, v39, v46, v43
	v_lshlrev_b32_e32 v33, 16, v8
	v_add_f32 v42, v42, v43
	v_and_b32_e32 v8, 0xffff0000, v8
	s_waitcnt vmcnt(16)
	v_sub_f32_e32 v32, v32, v12
	v_add_f32_dpp v42, v42, v42 row_ror:8 row_mask:0xf bank_mask:0xf bound_ctrl:1
	v_fma_f32 v32, v26, v32, v12
	v_mul_f32 v8, v32, v8
	v_lshlrev_b32_e32 v40, 16, v10
	v_add_f32_dpp v42, v42, v42 row_ror:4 row_mask:0xf bank_mask:0xf bound_ctrl:1
	v_and_b32_e32 v10, 0xffff0000, v10
	v_and_b32_e32 v9, 0xffff0000, v9
	v_add_f32_dpp v42, v42, v42 row_ror:2 row_mask:0xf bank_mask:0xf bound_ctrl:1
	v_and_b32_e32 v11, 0xffff0000, v11
	v_lshlrev_b32_e32 v41, 16, v4
	v_add_f32_dpp v43, v42, v42 row_ror:1 row_mask:0xf bank_mask:0xf bound_ctrl:1
	v_fma_f32 v8, v43, v9, v8
	v_and_b32_e32 v4, 0xffff0000, v4
	v_fma_f32 v14, v14, v0, v8
	v_mul_f32 v0, v32, v10
	v_and_b32_e32 v5, 0xffff0000, v5
	v_fma_f32 v0, v43, v11, v0
	v_lshlrev_b32_e32 v44, 16, v6
	v_fma_f32 v15, v15, v1, v0
	v_mul_f32 v0, v32, v4
	v_and_b32_e32 v6, 0xffff0000, v6
	v_fma_f32 v0, v43, v5, v0
	v_and_b32_e32 v7, 0xffff0000, v7
	v_fma_f32 v42, v38, v2, v0
	v_mul_f32 v0, v32, v6
	s_nop 0
	v_fma_f32 v0, v43, v7, v0
	v_mul_f32 v1, v42, v41
	s_nop 0
	v_fma_f32 v43, v39, v3, v0
	v_mul_f32 v0, v14, v33
	s_nop 0
	v_fma_f32 v0, v15, v40, v0
	v_fma_f32 v1, v43, v44, v1
	s_nop 0
	v_add_f32 v0, v0, v1
	v_mov_b32_e32 v1, 0
	s_nop 0
	v_add_f32_dpp v0, v0, v0 row_ror:8 row_mask:0xf bank_mask:0xf bound_ctrl:1
	s_nop 1
	v_add_f32_dpp v0, v0, v0 row_ror:4 row_mask:0xf bank_mask:0xf bound_ctrl:1
	s_nop 1
	v_add_f32_dpp v0, v0, v0 row_ror:2 row_mask:0xf bank_mask:0xf bound_ctrl:1
	s_nop 1
	v_mov_b32_dpp v1, v0 row_ror:1 row_mask:0xf bank_mask:0xf
	s_and_saveexec_b64 s[16:17], s[12:13]
	s_cbranch_execz .LBB0_752
	s_lshl_b64 s[14:15], s[14:15], 12
	s_add_u32 s14, s20, s14
	s_addc_u32 s15, s21, s15
	s_lshl_b32 s18, s28, 2
	s_add_u32 s14, s14, s18
	s_addc_u32 s15, s15, 0
	v_add_f32_e32 v0, v0, v1
	global_store_dword v31, v0, s[14:15]
.LBB0_752:
	s_or_b64 exec, exec, s[16:17]
	s_add_i32 s16, s30, 0x2042
	s_ashr_i32 s17, s16, 31
	s_lshl_b64 s[14:15], s[16:17], 10
	v_mov_b32_e32 v0, s29
	v_or3_b32 v0, s14, v0, v16
	s_mul_i32 s14, s16, 0x3480
	v_or3_b32 v1, s15, 0, 0
	s_mul_hi_i32 s15, s16, 0x3480
	s_add_u32 s14, s2, s14
	v_lshl_add_u64 v[2:3], v[0:1], 3, s[8:9]
	s_addc_u32 s15, s3, s15
	s_waitcnt vmcnt(8)
	v_mov_b64_e32 v[38:39], v[180:181]
	v_mov_b64_e32 v[40:41], v[182:183]
	v_mov_b64_e32 v[44:45], v[184:185]
	v_mov_b64_e32 v[46:47], v[186:187]
	v_mov_b32_e32 v33, v204
	v_lshl_add_u64 v[0:1], v[0:1], 2, s[0:1]
	v_mov_b64_e32 v[48:49], v[188:189]
	v_mov_b64_e32 v[50:51], v[190:191]
	s_add_i32 s14, s31, 0x2042
	s_ashr_i32 s15, s14, 31
	v_mov_b32_e32 v2, s28
	s_lshl_b64 s[18:19], s[14:15], 10
	s_mul_i32 s35, s14, 0x3480
	v_or3_b32 v1, s19, 0, 0
	v_or3_b32 v0, s18, v2, v16
	s_mul_hi_i32 s34, s14, 0x3480
	s_add_u32 s18, s2, s35
	v_lshl_add_u64 v[2:3], v[0:1], 2, s[0:1]
	v_lshl_add_u64 v[8:9], v[0:1], 3, s[8:9]
	s_addc_u32 s19, s3, s34
	v_mov_b64_e32 v[4:5], v[196:197]
	v_mov_b64_e32 v[6:7], v[198:199]
	s_nop 0
	v_mov_b64_e32 v[0:1], v[200:201]
	v_mov_b64_e32 v[2:3], v[202:203]
	s_nop 0
	v_mov_b64_e32 v[8:9], v[192:193]
	v_mov_b64_e32 v[10:11], v[194:195]
	s_nop 0
	v_mov_b32_e32 v32, v205
	s_waitcnt vmcnt(15)
	v_lshlrev_b32_e32 v56, 16, v39
	v_lshlrev_b32_e32 v52, 16, v38
	s_waitcnt vmcnt(13)
	v_sub_f32_e32 v13, v13, v33
	v_lshlrev_b32_e32 v53, 16, v40
	v_lshlrev_b32_e32 v54, 16, v44
	v_lshlrev_b32_e32 v55, 16, v46
	v_and_b32_e32 v38, 0xffff0000, v38
	v_and_b32_e32 v40, 0xffff0000, v40
	v_and_b32_e32 v44, 0xffff0000, v44
	v_and_b32_e32 v46, 0xffff0000, v46
	v_lshlrev_b32_e32 v57, 16, v41
	v_lshlrev_b32_e32 v58, 16, v45
	v_fma_f32 v13, v27, v13, v33
	v_mul_f32 v56, v34, v56
	v_lshlrev_b32_e32 v59, 16, v47
	v_mul_f32 v58, v36, v58
	v_fma_f32 v56, v35, v57, v56
	v_mul_f32 v38, v13, v38
	v_mul_f32 v40, v13, v40
	v_mul_f32 v44, v13, v44
	v_mul_f32 v13, v13, v46
	s_nop 0
	v_fma_f32 v57, v37, v59, v58
	v_and_b32_e32 v39, 0xffff0000, v39
	v_add_f32 v46, v56, v57
	v_and_b32_e32 v41, 0xffff0000, v41
	v_and_b32_e32 v47, 0xffff0000, v47
	v_add_f32_dpp v46, v46, v46 row_ror:8 row_mask:0xf bank_mask:0xf bound_ctrl:1
	v_and_b32_e32 v45, 0xffff0000, v45
	s_nop 0
	v_add_f32_dpp v46, v46, v46 row_ror:4 row_mask:0xf bank_mask:0xf bound_ctrl:1
	s_nop 1
	v_add_f32_dpp v46, v46, v46 row_ror:2 row_mask:0xf bank_mask:0xf bound_ctrl:1
	s_nop 1
	v_add_f32_dpp v46, v46, v46 row_ror:1 row_mask:0xf bank_mask:0xf bound_ctrl:1
	v_fma_f32 v38, v46, v39, v38
	v_fma_f32 v13, v46, v47, v13
	v_fma_f32 v39, v46, v41, v40
	v_fma_f32 v40, v46, v45, v44
	s_waitcnt vmcnt(12)
	v_fma_f32 v38, v34, v48, v38
	v_fma_f32 v41, v37, v51, v13
	v_fma_f32 v39, v35, v49, v39
	v_fma_f32 v40, v36, v50, v40
	s_nop 0
	v_mul_f32 v13, v38, v52
	v_mul_f32 v34, v40, v54
	s_nop 0
	v_fma_f32 v13, v39, v53, v13
	v_fma_f32 v34, v41, v55, v34
	s_nop 0
	v_add_f32 v13, v13, v34
	v_mov_b32_e32 v34, 0
	s_nop 0
	v_add_f32_dpp v13, v13, v13 row_ror:8 row_mask:0xf bank_mask:0xf bound_ctrl:1
	s_nop 1
	v_add_f32_dpp v13, v13, v13 row_ror:4 row_mask:0xf bank_mask:0xf bound_ctrl:1
	s_nop 1
	v_add_f32_dpp v13, v13, v13 row_ror:2 row_mask:0xf bank_mask:0xf bound_ctrl:1
	s_nop 1
	v_mov_b32_dpp v34, v13 row_ror:1 row_mask:0xf bank_mask:0xf
	s_and_saveexec_b64 s[18:19], s[6:7]
	s_cbranch_execz .LBB0_754
	s_lshl_b64 s[16:17], s[16:17], 12
	s_add_u32 s16, s20, s16
	s_addc_u32 s17, s21, s17
	s_lshl_b32 s34, s29, 2
	s_add_u32 s16, s16, s34
	s_addc_u32 s17, s17, 0
	v_add_f32_e32 v13, v13, v34
	global_store_dword v30, v13, s[16:17]
.LBB0_754:
	s_or_b64 exec, exec, s[18:19]
	s_waitcnt vmcnt(9)
	v_lshlrev_b32_e32 v34, 16, v9
	v_lshlrev_b32_e32 v35, 16, v11
	v_mul_f32 v34, v14, v34
	v_lshlrev_b32_e32 v36, 16, v5
	v_fma_f32 v34, v15, v35, v34
	v_mul_f32 v35, v42, v36
	v_lshlrev_b32_e32 v37, 16, v7
	v_fma_f32 v35, v43, v37, v35
	v_lshlrev_b32_e32 v13, 16, v8
	v_add_f32 v34, v34, v35
	v_and_b32_e32 v8, 0xffff0000, v8
	s_waitcnt vmcnt(8)
	v_sub_f32_e32 v12, v12, v32
	v_add_f32_dpp v34, v34, v34 row_ror:8 row_mask:0xf bank_mask:0xf bound_ctrl:1
	v_fma_f32 v12, v26, v12, v32
	v_mul_f32 v8, v12, v8
	v_lshlrev_b32_e32 v44, 16, v10
	v_add_f32_dpp v34, v34, v34 row_ror:4 row_mask:0xf bank_mask:0xf bound_ctrl:1
	v_and_b32_e32 v10, 0xffff0000, v10
	v_and_b32_e32 v9, 0xffff0000, v9
	v_add_f32_dpp v34, v34, v34 row_ror:2 row_mask:0xf bank_mask:0xf bound_ctrl:1
	v_and_b32_e32 v11, 0xffff0000, v11
	v_lshlrev_b32_e32 v45, 16, v4
	v_add_f32_dpp v37, v34, v34 row_ror:1 row_mask:0xf bank_mask:0xf bound_ctrl:1
	v_fma_f32 v8, v37, v9, v8
	v_and_b32_e32 v4, 0xffff0000, v4
	v_fma_f32 v34, v14, v0, v8
	v_mul_f32 v0, v12, v10
	v_and_b32_e32 v5, 0xffff0000, v5
	v_fma_f32 v0, v37, v11, v0
	v_lshlrev_b32_e32 v46, 16, v6
	v_fma_f32 v35, v15, v1, v0
	v_mul_f32 v0, v12, v4
	v_and_b32_e32 v6, 0xffff0000, v6
	v_fma_f32 v0, v37, v5, v0
	v_and_b32_e32 v7, 0xffff0000, v7
	v_fma_f32 v36, v42, v2, v0
	v_mul_f32 v0, v12, v6
	s_nop 0
	v_fma_f32 v0, v37, v7, v0
	v_mul_f32 v1, v36, v45
	s_nop 0
	v_fma_f32 v37, v43, v3, v0
	v_mul_f32 v0, v34, v13
	s_nop 0
	v_fma_f32 v0, v35, v44, v0
	v_fma_f32 v1, v37, v46, v1
	s_nop 0
	v_add_f32 v0, v0, v1
	v_mov_b32_e32 v1, 0
	s_nop 0
	v_add_f32_dpp v0, v0, v0 row_ror:8 row_mask:0xf bank_mask:0xf bound_ctrl:1
	s_nop 1
	v_add_f32_dpp v0, v0, v0 row_ror:4 row_mask:0xf bank_mask:0xf bound_ctrl:1
	s_nop 1
	v_add_f32_dpp v0, v0, v0 row_ror:2 row_mask:0xf bank_mask:0xf bound_ctrl:1
	s_nop 1
	v_mov_b32_dpp v1, v0 row_ror:1 row_mask:0xf bank_mask:0xf
	s_and_saveexec_b64 s[16:17], s[12:13]
	s_cbranch_execz .LBB0_756
	s_lshl_b64 s[14:15], s[14:15], 12
	s_add_u32 s14, s20, s14
	s_addc_u32 s15, s21, s15
	s_lshl_b32 s18, s28, 2
	s_add_u32 s14, s14, s18
	s_addc_u32 s15, s15, 0
	v_add_f32_e32 v0, v0, v1
	global_store_dword v31, v0, s[14:15]
.LBB0_756:
	s_or_b64 exec, exec, s[16:17]
	s_add_i32 s16, s30, 0x2043
	s_ashr_i32 s17, s16, 31
	s_lshl_b64 s[14:15], s[16:17], 10
	v_mov_b32_e32 v0, s29
	v_or3_b32 v0, s14, v0, v16
	s_mul_i32 s14, s16, 0x3480
	v_or3_b32 v1, s15, 0, 0
	s_mul_hi_i32 s15, s16, 0x3480
	s_add_u32 s14, s2, s14
	v_lshl_add_u64 v[2:3], v[0:1], 3, s[8:9]
	s_addc_u32 s15, s3, s15
	s_waitcnt vmcnt(0)
	v_mov_b64_e32 v[4:5], v[210:211]
	v_mov_b64_e32 v[6:7], v[212:213]
	v_mov_b64_e32 v[42:43], v[214:215]
	v_mov_b64_e32 v[44:45], v[216:217]
	v_mov_b32_e32 v50, v234
	v_lshl_add_u64 v[0:1], v[0:1], 2, s[0:1]
	v_mov_b64_e32 v[46:47], v[218:219]
	v_mov_b64_e32 v[48:49], v[220:221]
	s_add_i32 s14, s31, 0x2043
	s_ashr_i32 s15, s14, 31
	v_mov_b32_e32 v2, s28
	s_lshl_b64 s[18:19], s[14:15], 10
	s_mul_i32 s31, s14, 0x3480
	v_or3_b32 v1, s19, 0, 0
	v_or3_b32 v0, s18, v2, v16
	s_mul_hi_i32 s30, s14, 0x3480
	s_add_u32 s18, s2, s31
	v_lshl_add_u64 v[2:3], v[0:1], 2, s[0:1]
	v_lshl_add_u64 v[12:13], v[0:1], 3, s[8:9]
	s_addc_u32 s19, s3, s30
	v_mov_b64_e32 v[8:9], v[226:227]
	v_mov_b64_e32 v[10:11], v[228:229]
	s_nop 0
	v_mov_b64_e32 v[0:1], v[230:231]
	v_mov_b64_e32 v[2:3], v[232:233]
	s_nop 0
	v_mov_b64_e32 v[12:13], v[222:223]
	v_mov_b64_e32 v[14:15], v[224:225]
	s_nop 0
	v_mov_b32_e32 v28, v235
	s_waitcnt vmcnt(7)
	v_lshlrev_b32_e32 v54, 16, v5
	v_lshlrev_b32_e32 v55, 16, v7
	s_waitcnt vmcnt(5)
	v_sub_f32_e32 v33, v33, v50
	v_fmac_f32_e32 v50, v27, v33
	v_mul_f32 v27, v38, v54
	v_lshlrev_b32_e32 v56, 16, v43
	v_mul_f32 v33, v40, v56
	v_fma_f32 v27, v39, v55, v27
	v_lshlrev_b32_e32 v57, 16, v45
	v_fma_f32 v33, v41, v57, v33
	v_lshlrev_b32_e32 v29, 16, v4
	v_add_f32 v27, v27, v33
	v_and_b32_e32 v4, 0xffff0000, v4
	v_lshlrev_b32_e32 v51, 16, v6
	v_add_f32_dpp v27, v27, v27 row_ror:8 row_mask:0xf bank_mask:0xf bound_ctrl:1
	v_and_b32_e32 v6, 0xffff0000, v6
	v_mul_f32 v4, v50, v4
	v_lshlrev_b32_e32 v52, 16, v42
	v_add_f32_dpp v27, v27, v27 row_ror:4 row_mask:0xf bank_mask:0xf bound_ctrl:1
	v_lshlrev_b32_e32 v53, 16, v44
	v_and_b32_e32 v42, 0xffff0000, v42
	v_add_f32_dpp v27, v27, v27 row_ror:2 row_mask:0xf bank_mask:0xf bound_ctrl:1
	v_and_b32_e32 v44, 0xffff0000, v44
	v_and_b32_e32 v5, 0xffff0000, v5
	v_and_b32_e32 v7, 0xffff0000, v7
	v_mul_f32 v6, v50, v6
	v_add_f32_dpp v27, v27, v27 row_ror:1 row_mask:0xf bank_mask:0xf bound_ctrl:1
	v_fma_f32 v4, v27, v5, v4
	v_and_b32_e32 v43, 0xffff0000, v43
	v_and_b32_e32 v45, 0xffff0000, v45
	v_mul_f32 v42, v50, v42
	v_mul_f32 v44, v50, v44
	v_fma_f32 v5, v27, v7, v6
	s_waitcnt vmcnt(4)
	v_fma_f32 v4, v38, v46, v4
	v_fma_f32 v6, v27, v43, v42
	v_fma_f32 v7, v27, v45, v44
	s_nop 0
	v_mul_f32 v27, v4, v29
	v_fma_f32 v5, v39, v47, v5
	v_fma_f32 v6, v40, v48, v6
	s_nop 0
	v_fma_f32 v27, v5, v51, v27
	v_fma_f32 v7, v41, v49, v7
	v_mul_f32 v29, v6, v52
	s_nop 0
	v_fma_f32 v29, v7, v53, v29
	s_nop 0
	v_add_f32 v27, v27, v29
	v_mov_b32_e32 v29, 0
	s_nop 0
	v_add_f32_dpp v27, v27, v27 row_ror:8 row_mask:0xf bank_mask:0xf bound_ctrl:1
	s_nop 1
	v_add_f32_dpp v27, v27, v27 row_ror:4 row_mask:0xf bank_mask:0xf bound_ctrl:1
	s_nop 1
	v_add_f32_dpp v27, v27, v27 row_ror:2 row_mask:0xf bank_mask:0xf bound_ctrl:1
	s_nop 1
	v_mov_b32_dpp v29, v27 row_ror:1 row_mask:0xf bank_mask:0xf
	s_and_saveexec_b64 s[18:19], s[6:7]
	s_cbranch_execz .LBB0_758
	s_lshl_b64 s[16:17], s[16:17], 12
	s_add_u32 s16, s20, s16
	s_addc_u32 s17, s21, s17
	s_lshl_b32 s29, s29, 2
	s_add_u32 s16, s16, s29
	s_addc_u32 s17, s17, 0
	v_add_f32_e32 v27, v27, v29
	global_store_dword v30, v27, s[16:17]

.LBB0_802:
	s_ashr_i32 s29, s2, 8
	s_lshl_b32 s10, s29, 10
	s_and_b32 s28, s25, 0x3c0
	v_readlane_b32 s36, v245, 6
	s_or_b32 s34, s28, s10
	s_mul_i32 s11, s29, 0x3480
	v_readlane_b32 s40, v245, 10
	s_mul_hi_i32 s10, s29, 0x3480
	v_readlane_b32 s41, v245, 11
	s_add_u32 s14, s40, s11
	s_addc_u32 s15, s41, s10
	s_add_i32 s18, s3, s2
	s_cmpk_lt_i32 s18, 0x3000
	s_cselect_b64 s[10:11], -1, 0
	s_cmpk_gt_i32 s18, 0x2fff
	s_cselect_b64 s[12:13], -1, 0
	s_and_b64 s[16:17], s[12:13], exec
	s_cselect_b32 s16, s2, s18
	s_ashr_i32 s35, s16, 8
	s_lshl_b32 s36, s16, 2
	v_readlane_b32 s37, v245, 7
	s_lshl_b32 s16, s35, 10
	s_and_b32 s27, s36, 0x3c0
	s_or_b32 s37, s27, s16
	s_mul_i32 s17, s35, 0x3480
	s_mul_hi_i32 s16, s35, 0x3480
	s_add_u32 s18, s40, s17
	s_addc_u32 s19, s41, s16
	s_lshl_b32 s29, s29, 2
	s_add_i32 s16, s29, 0x2040
	s_ashr_i32 s17, s16, 31
	s_lshl_b64 s[30:31], s[16:17], 10
	s_or_b32 s30, s30, s28
	v_mov_b32_e32 v5, s31
	v_or_b32_e32 v4, s30, v16
	v_lshl_add_u64 v[0:1], v[4:5], 3, s[8:9]
	v_and_or_b32 v29, s25, 60, v61
	global_load_dwordx4 v[38:41], v[0:1], off
	global_load_dwordx4 v[42:45], v[0:1], off offset:16
	v_or_b32_e32 v0, s34, v29
	v_ashrrev_i32_e32 v1, 31, v0
	v_readlane_b32 s42, v245, 12
	v_readlane_b32 s43, v245, 13
	v_readlane_b32 s44, v245, 14
	v_readlane_b32 s45, v245, 15
	v_readlane_b32 s46, v245, 16
	v_readlane_b32 s47, v245, 17
	v_readlane_b32 s48, v245, 18
	v_readlane_b32 s49, v245, 19
	v_readlane_b32 s50, v245, 20
	v_readlane_b32 s51, v245, 21
	v_lshlrev_b64 v[22:23], 8, v[0:1]
	v_or_b32_e32 v0, s28, v29
	v_or_b32_e32 v0, 0x800, v0
	s_mul_i32 s30, s16, 0x3480
	v_readlane_b32 s40, v245, 22
	v_lshlrev_b32_e32 v27, 2, v0
	s_mul_hi_i32 s31, s16, 0x3480
	s_add_u32 s30, s20, s30
	v_readlane_b32 s41, v245, 23
	s_addc_u32 s31, s21, s31
	s_nop 3
	global_load_dword v26, v27, s[40:41]
	global_load_dword v33, v27, s[14:15]
	global_load_dword v32, v27, s[30:31]
	s_lshl_b32 s30, s35, 2
	s_add_i32 s14, s30, 0x2040
	v_lshl_add_u64 v[0:1], v[18:19], 0, v[22:23]
	v_and_or_b32 v30, s36, 60, v61
	s_ashr_i32 s15, s14, 31
	global_load_dwordx4 v[46:49], v[0:1], off
	v_or_b32_e32 v0, s37, v30
	s_lshl_b64 s[34:35], s[14:15], 10
	v_ashrrev_i32_e32 v1, 31, v0
	v_or_b32_e32 v6, s27, v30
	v_lshl_add_u64 v[4:5], v[4:5], 2, s[6:7]
	s_or_b32 s31, s34, s27
	v_lshlrev_b64 v[24:25], 8, v[0:1]
	v_or_b32_e32 v6, 0x800, v6
	global_load_dwordx4 v[50:53], v[4:5], off
	v_mov_b32_e32 v5, s35
	v_or_b32_e32 v4, s31, v16
	s_mul_i32 s34, s14, 0x3480
	v_lshl_add_u64 v[0:1], v[18:19], 0, v[24:25]
	v_lshlrev_b32_e32 v28, 2, v6
	v_lshl_add_u64 v[6:7], v[4:5], 2, s[6:7]
	v_lshl_add_u64 v[12:13], v[4:5], 3, s[8:9]
	s_mul_hi_i32 s31, s14, 0x3480
	s_add_u32 s34, s20, s34
	global_load_dwordx4 v[0:3], v[0:1], off
	s_nop 0
	global_load_dwordx4 v[8:11], v[12:13], off offset:16
	s_nop 0
	global_load_dwordx4 v[4:7], v[6:7], off
	s_nop 0
	global_load_dwordx4 v[12:15], v[12:13], off
	s_addc_u32 s35, s21, s31
	global_load_dword v17, v28, s[40:41]
	global_load_dword v37, v28, s[18:19]
	global_load_dword v31, v28, s[34:35]
	s_add_i32 s64, s29, 0x2041
	s_ashr_i32 s65, s64, 31
	s_lshl_b64 s[66:67], s[64:65], 10
	v_mov_b32_e32 v236, s28
	v_or3_b32 v236, s66, v236, v16
	v_or3_b32 v237, s67, 0, 0
	s_mul_hi_i32 s67, s64, 0x3480
	s_mul_i32 s66, s64, 0x3480
	s_add_u32 s66, s20, s66
	s_addc_u32 s67, s21, s67
	v_lshl_add_u64 v[238:239], v[236:237], 3, s[8:9]
	global_load_dwordx4 v[148:151], v[238:239], off
	global_load_dwordx4 v[152:155], v[238:239], off offset:16
	global_load_dword v172, v27, s[66:67]
	v_lshl_add_u64 v[238:239], v[236:237], 2, s[6:7]
	global_load_dwordx4 v[156:159], v[238:239], off
	s_add_i32 s64, s30, 0x2041
	s_ashr_i32 s65, s64, 31
	s_lshl_b64 s[66:67], s[64:65], 10
	v_mov_b32_e32 v236, s27
	v_or3_b32 v236, s66, v236, v16
	v_or3_b32 v237, s67, 0, 0
	s_mul_hi_i32 s67, s64, 0x3480
	s_mul_i32 s66, s64, 0x3480
	s_add_u32 s66, s20, s66
	s_addc_u32 s67, s21, s67
	v_lshl_add_u64 v[238:239], v[236:237], 3, s[8:9]
	global_load_dwordx4 v[160:163], v[238:239], off
	global_load_dwordx4 v[164:167], v[238:239], off offset:16
	global_load_dword v173, v28, s[66:67]
	v_lshl_add_u64 v[238:239], v[236:237], 2, s[6:7]
	global_load_dwordx4 v[168:171], v[238:239], off
	s_add_i32 s64, s29, 0x2042
	s_ashr_i32 s65, s64, 31
	s_lshl_b64 s[66:67], s[64:65], 10
	v_mov_b32_e32 v236, s28
	v_or3_b32 v236, s66, v236, v16
	v_or3_b32 v237, s67, 0, 0
	s_mul_hi_i32 s67, s64, 0x3480
	s_mul_i32 s66, s64, 0x3480
	s_add_u32 s66, s20, s66
	s_addc_u32 s67, s21, s67
	v_lshl_add_u64 v[238:239], v[236:237], 3, s[8:9]
	global_load_dwordx4 v[180:183], v[238:239], off
	global_load_dwordx4 v[184:187], v[238:239], off offset:16
	global_load_dword v204, v27, s[66:67]
	v_lshl_add_u64 v[238:239], v[236:237], 2, s[6:7]
	global_load_dwordx4 v[188:191], v[238:239], off
	s_add_i32 s64, s30, 0x2042
	s_ashr_i32 s65, s64, 31
	s_lshl_b64 s[66:67], s[64:65], 10
	v_mov_b32_e32 v236, s27
	v_or3_b32 v236, s66, v236, v16
	v_or3_b32 v237, s67, 0, 0
	s_mul_hi_i32 s67, s64, 0x3480
	s_mul_i32 s66, s64, 0x3480
	s_add_u32 s66, s20, s66
	s_addc_u32 s67, s21, s67
	v_lshl_add_u64 v[238:239], v[236:237], 3, s[8:9]
	global_load_dwordx4 v[192:195], v[238:239], off
	global_load_dwordx4 v[196:199], v[238:239], off offset:16
	global_load_dword v205, v28, s[66:67]
	v_lshl_add_u64 v[238:239], v[236:237], 2, s[6:7]
	global_load_dwordx4 v[200:203], v[238:239], off
	s_add_i32 s64, s29, 0x2043
	s_ashr_i32 s65, s64, 31
	s_lshl_b64 s[66:67], s[64:65], 10
	v_mov_b32_e32 v236, s28
	v_or3_b32 v236, s66, v236, v16
	v_or3_b32 v237, s67, 0, 0
	s_mul_hi_i32 s67, s64, 0x3480
	s_mul_i32 s66, s64, 0x3480
	s_add_u32 s66, s20, s66
	s_addc_u32 s67, s21, s67
	v_lshl_add_u64 v[238:239], v[236:237], 3, s[8:9]
	global_load_dwordx4 v[210:213], v[238:239], off
	global_load_dwordx4 v[214:217], v[238:239], off offset:16
	global_load_dword v234, v27, s[66:67]
	v_lshl_add_u64 v[238:239], v[236:237], 2, s[6:7]
	global_load_dwordx4 v[218:221], v[238:239], off
	s_add_i32 s64, s30, 0x2043
	s_ashr_i32 s65, s64, 31
	s_lshl_b64 s[66:67], s[64:65], 10
	v_mov_b32_e32 v236, s27
	v_or3_b32 v236, s66, v236, v16
	v_or3_b32 v237, s67, 0, 0
	s_mul_hi_i32 s67, s64, 0x3480
	s_mul_i32 s66, s64, 0x3480
	s_add_u32 s66, s20, s66
	s_addc_u32 s67, s21, s67
	v_lshl_add_u64 v[238:239], v[236:237], 3, s[8:9]
	global_load_dwordx4 v[222:225], v[238:239], off
	global_load_dwordx4 v[226:229], v[238:239], off offset:16
	global_load_dword v235, v28, s[66:67]
	v_lshl_add_u64 v[238:239], v[236:237], 2, s[6:7]
	global_load_dwordx4 v[230:233], v[238:239], off
	v_lshlrev_b32_e32 v29, 2, v29
	v_readlane_b32 s38, v245, 8
	v_readlane_b32 s39, v245, 9
	v_readlane_b32 s42, v245, 24
	v_readlane_b32 s43, v245, 25
	v_readlane_b32 s44, v245, 26
	v_readlane_b32 s45, v245, 27
	v_readlane_b32 s46, v245, 28
	v_readlane_b32 s47, v245, 29
	v_readlane_b32 s48, v245, 30
	v_readlane_b32 s49, v245, 31
	v_readlane_b32 s50, v245, 32
	v_readlane_b32 s51, v245, 33
	v_readlane_b32 s52, v245, 34
	v_readlane_b32 s53, v245, 35
	v_readlane_b32 s54, v245, 36
	v_readlane_b32 s55, v245, 37
	s_waitcnt vmcnt(37)
	v_lshlrev_b32_e32 v55, 16, v40
	v_and_b32_e32 v35, 0xffff0000, v40
	v_lshlrev_b32_e32 v40, 16, v39
	v_lshlrev_b32_e32 v54, 16, v38
	s_waitcnt vmcnt(36)
	v_lshlrev_b32_e32 v56, 16, v42
	v_lshlrev_b32_e32 v57, 16, v44
	v_and_b32_e32 v34, 0xffff0000, v38
	v_and_b32_e32 v36, 0xffff0000, v42
	v_and_b32_e32 v38, 0xffff0000, v44
	v_lshlrev_b32_e32 v42, 16, v41
	v_lshlrev_b32_e32 v44, 16, v43
	v_lshlrev_b32_e32 v58, 16, v45
	v_and_b32_e32 v39, 0xffff0000, v39
	v_and_b32_e32 v41, 0xffff0000, v41
	v_and_b32_e32 v43, 0xffff0000, v43
	v_and_b32_e32 v45, 0xffff0000, v45
	s_waitcnt vmcnt(33)
	v_sub_f32_e32 v33, v33, v32
	v_fma_f32 v59, v26, v33, v32
	s_waitcnt vmcnt(32)
	v_mul_f32 v33, v46, v40
	v_mul_f32 v40, v48, v44
	v_mul_f32 v34, v59, v34
	v_mul_f32 v35, v59, v35
	s_nop 0
	v_fma_f32 v33, v47, v42, v33
	v_fma_f32 v40, v49, v58, v40
	s_nop 0
	v_add_f32 v33, v33, v40
	s_nop 1
	v_add_f32_dpp v33, v33, v33 row_ror:8 row_mask:0xf bank_mask:0xf bound_ctrl:1
	s_nop 1
	v_add_f32_dpp v33, v33, v33 row_ror:4 row_mask:0xf bank_mask:0xf bound_ctrl:1
	s_nop 1
	v_add_f32_dpp v33, v33, v33 row_ror:2 row_mask:0xf bank_mask:0xf bound_ctrl:1
	s_nop 1
	v_add_f32_dpp v40, v33, v33 row_ror:1 row_mask:0xf bank_mask:0xf bound_ctrl:1
	v_fma_f32 v33, v40, v39, v34
	v_fma_f32 v34, v40, v41, v35
	v_mul_f32 v35, v59, v36
	v_mul_f32 v36, v59, v38
	s_waitcnt vmcnt(31)
	v_fma_f32 v33, v46, v50, v33
	v_fma_f32 v35, v40, v43, v35
	v_fma_f32 v34, v47, v51, v34
	v_fma_f32 v36, v40, v45, v36
	s_nop 0
	v_mul_f32 v38, v33, v54
	v_fma_f32 v35, v48, v52, v35
	v_fma_f32 v36, v49, v53, v36
	s_nop 0
	v_fma_f32 v38, v34, v55, v38
	v_mul_f32 v39, v35, v56
	s_nop 0
	v_fma_f32 v39, v36, v57, v39
	s_nop 0
	v_add_f32 v38, v38, v39
	v_mov_b32_e32 v39, 0
	s_nop 0
	v_add_f32_dpp v38, v38, v38 row_ror:8 row_mask:0xf bank_mask:0xf bound_ctrl:1
	s_nop 1
	v_add_f32_dpp v38, v38, v38 row_ror:4 row_mask:0xf bank_mask:0xf bound_ctrl:1
	s_nop 1
	v_add_f32_dpp v38, v38, v38 row_ror:2 row_mask:0xf bank_mask:0xf bound_ctrl:1
	s_nop 1
	v_mov_b32_dpp v39, v38 row_ror:1 row_mask:0xf bank_mask:0xf
	s_and_saveexec_b64 s[18:19], s[4:5]
	s_cbranch_execz .LBB0_804
	s_lshl_b64 s[16:17], s[16:17], 12
	s_add_u32 s16, s22, s16
	s_addc_u32 s17, s23, s17
	s_lshl_b32 s31, s28, 2
	s_add_u32 s16, s16, s31
	s_addc_u32 s17, s17, 0
	v_add_f32_e32 v38, v38, v39
	global_store_dword v29, v38, s[16:17]
.LBB0_804:
	s_or_b64 exec, exec, s[18:19]
	s_waitcnt vmcnt(27)
	v_lshlrev_b32_e32 v40, 16, v14
	v_and_b32_e32 v38, 0xffff0000, v14
	v_lshlrev_b32_e32 v14, 16, v13
	s_waitcnt vmcnt(24)
	v_sub_f32_e32 v37, v37, v31
	v_mul_f32 v14, v0, v14
	v_lshlrev_b32_e32 v43, 16, v15
	v_lshlrev_b32_e32 v44, 16, v9
	v_fma_f32 v46, v17, v37, v31
	v_fma_f32 v14, v1, v43, v14
	v_mul_f32 v37, v2, v44
	v_lshlrev_b32_e32 v45, 16, v11
	v_fma_f32 v37, v3, v45, v37
	v_lshlrev_b32_e32 v39, 16, v12
	v_add_f32 v14, v14, v37
	v_and_b32_e32 v12, 0xffff0000, v12
	v_mul_f32 v12, v46, v12
	v_and_b32_e32 v13, 0xffff0000, v13
	v_add_f32_dpp v14, v14, v14 row_ror:8 row_mask:0xf bank_mask:0xf bound_ctrl:1
	v_and_b32_e32 v15, 0xffff0000, v15
	v_lshlrev_b32_e32 v41, 16, v8
	v_add_f32_dpp v14, v14, v14 row_ror:4 row_mask:0xf bank_mask:0xf bound_ctrl:1
	v_and_b32_e32 v8, 0xffff0000, v8
	v_and_b32_e32 v9, 0xffff0000, v9
	v_add_f32_dpp v14, v14, v14 row_ror:2 row_mask:0xf bank_mask:0xf bound_ctrl:1
	v_lshlrev_b32_e32 v42, 16, v10
	v_and_b32_e32 v10, 0xffff0000, v10
	v_add_f32_dpp v43, v14, v14 row_ror:1 row_mask:0xf bank_mask:0xf bound_ctrl:1
	v_fma_f32 v12, v43, v13, v12
	v_and_b32_e32 v11, 0xffff0000, v11
	v_fma_f32 v14, v0, v4, v12
	v_mul_f32 v0, v46, v38
	s_nor_b64 s[12:13], s[0:1], s[12:13]
	v_fma_f32 v0, v43, v15, v0
	v_lshlrev_b32_e32 v30, 2, v30
	v_fma_f32 v15, v1, v5, v0
	v_mul_f32 v0, v46, v8
	s_nop 0
	v_fma_f32 v0, v43, v9, v0
	s_nop 0
	v_fma_f32 v37, v2, v6, v0
	v_mul_f32 v0, v46, v10
	s_nop 0
	v_fma_f32 v0, v43, v11, v0
	v_mul_f32 v1, v37, v41
	s_nop 0
	v_fma_f32 v38, v3, v7, v0
	v_mul_f32 v0, v14, v39
	s_nop 0
	v_fma_f32 v0, v15, v40, v0
	v_fma_f32 v1, v38, v42, v1
	s_nop 0
	v_add_f32 v0, v0, v1
	v_mov_b32_e32 v1, 0
	s_nop 0
	v_add_f32_dpp v0, v0, v0 row_ror:8 row_mask:0xf bank_mask:0xf bound_ctrl:1
	s_nop 1
	v_add_f32_dpp v0, v0, v0 row_ror:4 row_mask:0xf bank_mask:0xf bound_ctrl:1
	s_nop 1
	v_add_f32_dpp v0, v0, v0 row_ror:2 row_mask:0xf bank_mask:0xf bound_ctrl:1
	s_nop 1
	v_mov_b32_dpp v1, v0 row_ror:1 row_mask:0xf bank_mask:0xf
	s_and_saveexec_b64 s[16:17], s[12:13]
	s_cbranch_execz .LBB0_806
	s_lshl_b64 s[14:15], s[14:15], 12
	s_add_u32 s14, s22, s14
	s_addc_u32 s15, s23, s15
	s_lshl_b32 s18, s27, 2
	s_add_u32 s14, s14, s18
	s_addc_u32 s15, s15, 0
	v_add_f32_e32 v0, v0, v1
	global_store_dword v30, v0, s[14:15]
.LBB0_806:
	s_or_b64 exec, exec, s[16:17]
	s_add_i32 s16, s29, 0x2041
	s_ashr_i32 s17, s16, 31
	s_lshl_b64 s[14:15], s[16:17], 10
	v_mov_b32_e32 v0, s28
	v_or3_b32 v0, s14, v0, v16
	s_mul_i32 s14, s16, 0x3480
	v_or3_b32 v1, s15, 0, 0
	s_mul_hi_i32 s15, s16, 0x3480
	s_add_u32 s14, s20, s14
	v_lshl_add_u64 v[2:3], v[0:1], 3, s[8:9]
	s_addc_u32 s15, s21, s15
	s_waitcnt vmcnt(16)
	v_mov_b64_e32 v[40:41], v[148:149]
	v_mov_b64_e32 v[42:43], v[150:151]
	v_mov_b64_e32 v[44:45], v[152:153]
	v_mov_b64_e32 v[46:47], v[154:155]
	v_mov_b32_e32 v13, v172
	v_lshl_add_u64 v[0:1], v[0:1], 2, s[6:7]
	v_mov_b64_e32 v[48:49], v[156:157]
	v_mov_b64_e32 v[50:51], v[158:159]
	s_add_i32 s14, s30, 0x2041
	s_ashr_i32 s15, s14, 31
	v_mov_b32_e32 v2, s27
	s_lshl_b64 s[18:19], s[14:15], 10
	s_mul_i32 s34, s14, 0x3480
	v_or3_b32 v1, s19, 0, 0
	v_or3_b32 v0, s18, v2, v16
	s_mul_hi_i32 s31, s14, 0x3480
	s_add_u32 s18, s20, s34
	v_lshl_add_u64 v[2:3], v[0:1], 2, s[6:7]
	v_lshl_add_u64 v[8:9], v[0:1], 3, s[8:9]
	s_addc_u32 s19, s21, s31
	v_mov_b64_e32 v[4:5], v[164:165]
	v_mov_b64_e32 v[6:7], v[166:167]
	s_nop 0
	v_mov_b64_e32 v[0:1], v[168:169]
	v_mov_b64_e32 v[2:3], v[170:171]
	s_nop 0
	v_mov_b64_e32 v[8:9], v[160:161]
	v_mov_b64_e32 v[10:11], v[162:163]
	s_nop 0
	v_mov_b32_e32 v12, v173
	s_waitcnt vmcnt(23)
	v_lshlrev_b32_e32 v55, 16, v41
	v_lshlrev_b32_e32 v39, 16, v40
	s_waitcnt vmcnt(21)
	v_sub_f32_e32 v32, v32, v13
	v_lshlrev_b32_e32 v52, 16, v42
	v_lshlrev_b32_e32 v53, 16, v44
	v_lshlrev_b32_e32 v54, 16, v46
	v_and_b32_e32 v40, 0xffff0000, v40
	v_and_b32_e32 v42, 0xffff0000, v42
	v_and_b32_e32 v44, 0xffff0000, v44
	v_and_b32_e32 v46, 0xffff0000, v46
	v_lshlrev_b32_e32 v56, 16, v43
	v_lshlrev_b32_e32 v57, 16, v45
	v_fma_f32 v32, v26, v32, v13
	v_mul_f32 v55, v33, v55
	v_lshlrev_b32_e32 v58, 16, v47
	v_mul_f32 v57, v35, v57
	v_fma_f32 v55, v34, v56, v55
	v_mul_f32 v40, v32, v40
	v_mul_f32 v42, v32, v42
	v_mul_f32 v44, v32, v44
	v_mul_f32 v32, v32, v46
	s_nop 0
	v_fma_f32 v56, v36, v58, v57
	v_and_b32_e32 v47, 0xffff0000, v47
	v_add_f32 v46, v55, v56
	v_and_b32_e32 v41, 0xffff0000, v41
	v_and_b32_e32 v43, 0xffff0000, v43
	v_add_f32_dpp v46, v46, v46 row_ror:8 row_mask:0xf bank_mask:0xf bound_ctrl:1
	v_and_b32_e32 v45, 0xffff0000, v45
	s_nop 0
	v_add_f32_dpp v46, v46, v46 row_ror:4 row_mask:0xf bank_mask:0xf bound_ctrl:1
	s_nop 1
	v_add_f32_dpp v46, v46, v46 row_ror:2 row_mask:0xf bank_mask:0xf bound_ctrl:1
	s_nop 1
	v_add_f32_dpp v46, v46, v46 row_ror:1 row_mask:0xf bank_mask:0xf bound_ctrl:1
	v_fma_f32 v32, v46, v47, v32
	v_fma_f32 v40, v46, v41, v40
	v_fma_f32 v41, v46, v43, v42
	v_fma_f32 v42, v46, v45, v44
	s_waitcnt vmcnt(20)
	v_fma_f32 v33, v33, v48, v40
	v_fma_f32 v36, v36, v51, v32
	v_fma_f32 v34, v34, v49, v41
	v_fma_f32 v35, v35, v50, v42
	s_nop 0
	v_mul_f32 v32, v33, v39
	v_mul_f32 v39, v35, v53
	s_nop 0
	v_fma_f32 v32, v34, v52, v32
	v_fma_f32 v39, v36, v54, v39
	s_nop 0
	v_add_f32 v32, v32, v39
	v_mov_b32_e32 v39, 0
	s_nop 0
	v_add_f32_dpp v32, v32, v32 row_ror:8 row_mask:0xf bank_mask:0xf bound_ctrl:1
	s_nop 1
	v_add_f32_dpp v32, v32, v32 row_ror:4 row_mask:0xf bank_mask:0xf bound_ctrl:1
	s_nop 1
	v_add_f32_dpp v32, v32, v32 row_ror:2 row_mask:0xf bank_mask:0xf bound_ctrl:1
	s_nop 1
	v_mov_b32_dpp v39, v32 row_ror:1 row_mask:0xf bank_mask:0xf
	s_and_saveexec_b64 s[18:19], s[4:5]
	s_cbranch_execz .LBB0_808
	s_lshl_b64 s[16:17], s[16:17], 12
	s_add_u32 s16, s22, s16
	s_addc_u32 s17, s23, s17
	s_lshl_b32 s31, s28, 2
	s_add_u32 s16, s16, s31
	s_addc_u32 s17, s17, 0
	v_add_f32_e32 v32, v32, v39
	global_store_dword v29, v32, s[16:17]
.LBB0_808:
	s_or_b64 exec, exec, s[18:19]
	s_waitcnt vmcnt(17)
	v_lshlrev_b32_e32 v41, 16, v9
	v_lshlrev_b32_e32 v42, 16, v11
	v_mul_f32 v41, v14, v41
	v_lshlrev_b32_e32 v44, 16, v5
	v_fma_f32 v41, v15, v42, v41
	v_mul_f32 v42, v37, v44
	v_lshlrev_b32_e32 v45, 16, v7
	v_fma_f32 v42, v38, v45, v42
	v_lshlrev_b32_e32 v32, 16, v8
	v_add_f32 v41, v41, v42
	v_and_b32_e32 v8, 0xffff0000, v8
	s_waitcnt vmcnt(16)
	v_sub_f32_e32 v31, v31, v12
	v_add_f32_dpp v41, v41, v41 row_ror:8 row_mask:0xf bank_mask:0xf bound_ctrl:1
	v_fma_f32 v31, v17, v31, v12
	v_mul_f32 v8, v31, v8
	v_lshlrev_b32_e32 v39, 16, v10
	v_add_f32_dpp v41, v41, v41 row_ror:4 row_mask:0xf bank_mask:0xf bound_ctrl:1
	v_and_b32_e32 v10, 0xffff0000, v10
	v_and_b32_e32 v9, 0xffff0000, v9
	v_add_f32_dpp v41, v41, v41 row_ror:2 row_mask:0xf bank_mask:0xf bound_ctrl:1
	v_and_b32_e32 v11, 0xffff0000, v11
	v_lshlrev_b32_e32 v40, 16, v4
	v_add_f32_dpp v42, v41, v41 row_ror:1 row_mask:0xf bank_mask:0xf bound_ctrl:1
	v_fma_f32 v8, v42, v9, v8
	v_and_b32_e32 v4, 0xffff0000, v4
	v_fma_f32 v14, v14, v0, v8
	v_mul_f32 v0, v31, v10
	v_and_b32_e32 v5, 0xffff0000, v5
	v_fma_f32 v0, v42, v11, v0
	v_lshlrev_b32_e32 v43, 16, v6
	v_fma_f32 v15, v15, v1, v0
	v_mul_f32 v0, v31, v4
	v_and_b32_e32 v6, 0xffff0000, v6
	v_fma_f32 v0, v42, v5, v0
	v_and_b32_e32 v7, 0xffff0000, v7
	v_fma_f32 v41, v37, v2, v0
	v_mul_f32 v0, v31, v6
	s_nop 0
	v_fma_f32 v0, v42, v7, v0
	v_mul_f32 v1, v41, v40
	s_nop 0
	v_fma_f32 v42, v38, v3, v0
	v_mul_f32 v0, v14, v32
	s_nop 0
	v_fma_f32 v0, v15, v39, v0
	v_fma_f32 v1, v42, v43, v1
	s_nop 0
	v_add_f32 v0, v0, v1
	v_mov_b32_e32 v1, 0
	s_nop 0
	v_add_f32_dpp v0, v0, v0 row_ror:8 row_mask:0xf bank_mask:0xf bound_ctrl:1
	s_nop 1
	v_add_f32_dpp v0, v0, v0 row_ror:4 row_mask:0xf bank_mask:0xf bound_ctrl:1
	s_nop 1
	v_add_f32_dpp v0, v0, v0 row_ror:2 row_mask:0xf bank_mask:0xf bound_ctrl:1
	s_nop 1
	v_mov_b32_dpp v1, v0 row_ror:1 row_mask:0xf bank_mask:0xf
	s_and_saveexec_b64 s[16:17], s[12:13]
	s_cbranch_execz .LBB0_810
	s_lshl_b64 s[14:15], s[14:15], 12
	s_add_u32 s14, s22, s14
	s_addc_u32 s15, s23, s15
	s_lshl_b32 s18, s27, 2
	s_add_u32 s14, s14, s18
	s_addc_u32 s15, s15, 0
	v_add_f32_e32 v0, v0, v1
	global_store_dword v30, v0, s[14:15]
.LBB0_810:
	s_or_b64 exec, exec, s[16:17]
	s_add_i32 s16, s29, 0x2042
	s_ashr_i32 s17, s16, 31
	s_lshl_b64 s[14:15], s[16:17], 10
	v_mov_b32_e32 v0, s28
	v_or3_b32 v0, s14, v0, v16
	s_mul_i32 s14, s16, 0x3480
	v_or3_b32 v1, s15, 0, 0
	s_mul_hi_i32 s15, s16, 0x3480
	s_add_u32 s14, s20, s14
	v_lshl_add_u64 v[2:3], v[0:1], 3, s[8:9]
	s_addc_u32 s15, s21, s15
	s_waitcnt vmcnt(8)
	v_mov_b64_e32 v[44:45], v[180:181]
	v_mov_b64_e32 v[46:47], v[182:183]
	v_mov_b64_e32 v[48:49], v[184:185]
	v_mov_b64_e32 v[50:51], v[186:187]
	v_mov_b32_e32 v32, v204
	v_lshl_add_u64 v[0:1], v[0:1], 2, s[6:7]
	v_mov_b64_e32 v[52:53], v[188:189]
	v_mov_b64_e32 v[54:55], v[190:191]
	s_add_i32 s14, s30, 0x2042
	s_ashr_i32 s15, s14, 31
	v_mov_b32_e32 v2, s27
	s_lshl_b64 s[18:19], s[14:15], 10
	s_mul_i32 s34, s14, 0x3480
	v_or3_b32 v1, s19, 0, 0
	v_or3_b32 v0, s18, v2, v16
	s_mul_hi_i32 s31, s14, 0x3480
	s_add_u32 s18, s20, s34
	v_lshl_add_u64 v[2:3], v[0:1], 2, s[6:7]
	v_lshl_add_u64 v[8:9], v[0:1], 3, s[8:9]
	s_addc_u32 s19, s21, s31
	v_mov_b64_e32 v[4:5], v[196:197]
	v_mov_b64_e32 v[6:7], v[198:199]
	s_nop 0
	v_mov_b64_e32 v[0:1], v[200:201]
	v_mov_b64_e32 v[2:3], v[202:203]
	s_nop 0
	v_mov_b64_e32 v[8:9], v[192:193]
	v_mov_b64_e32 v[10:11], v[194:195]
	s_nop 0
	v_mov_b32_e32 v31, v205
	s_waitcnt vmcnt(15)
	v_lshlrev_b32_e32 v43, 16, v44
	v_and_b32_e32 v37, 0xffff0000, v44
	v_lshlrev_b32_e32 v44, 16, v45
	s_waitcnt vmcnt(13)
	v_sub_f32_e32 v13, v13, v32
	v_lshlrev_b32_e32 v56, 16, v46
	v_lshlrev_b32_e32 v57, 16, v48
	v_and_b32_e32 v38, 0xffff0000, v46
	v_and_b32_e32 v39, 0xffff0000, v48
	v_and_b32_e32 v40, 0xffff0000, v50
	v_lshlrev_b32_e32 v46, 16, v47
	v_lshlrev_b32_e32 v48, 16, v49
	v_fma_f32 v13, v26, v13, v32
	v_mul_f32 v44, v33, v44
	v_lshlrev_b32_e32 v58, 16, v50
	v_lshlrev_b32_e32 v50, 16, v51
	v_mul_f32 v48, v35, v48
	v_fma_f32 v44, v34, v46, v44
	v_mul_f32 v37, v13, v37
	v_mul_f32 v38, v13, v38
	v_mul_f32 v39, v13, v39
	v_mul_f32 v13, v13, v40
	s_nop 0
	v_fma_f32 v46, v36, v50, v48
	v_and_b32_e32 v45, 0xffff0000, v45
	v_add_f32 v40, v44, v46
	v_and_b32_e32 v51, 0xffff0000, v51
	v_and_b32_e32 v47, 0xffff0000, v47
	v_add_f32_dpp v40, v40, v40 row_ror:8 row_mask:0xf bank_mask:0xf bound_ctrl:1
	v_and_b32_e32 v49, 0xffff0000, v49
	s_nop 0
	v_add_f32_dpp v40, v40, v40 row_ror:4 row_mask:0xf bank_mask:0xf bound_ctrl:1
	s_nop 1
	v_add_f32_dpp v40, v40, v40 row_ror:2 row_mask:0xf bank_mask:0xf bound_ctrl:1
	s_nop 1
	v_add_f32_dpp v40, v40, v40 row_ror:1 row_mask:0xf bank_mask:0xf bound_ctrl:1
	v_fma_f32 v37, v40, v45, v37
	v_fma_f32 v13, v40, v51, v13
	v_fma_f32 v38, v40, v47, v38
	v_fma_f32 v39, v40, v49, v39
	s_waitcnt vmcnt(12)
	v_fma_f32 v37, v33, v52, v37
	v_fma_f32 v40, v36, v55, v13
	v_fma_f32 v38, v34, v53, v38
	v_fma_f32 v39, v35, v54, v39
	s_nop 0
	v_mul_f32 v13, v37, v43
	v_mul_f32 v33, v39, v57
	s_nop 0
	v_fma_f32 v13, v38, v56, v13
	v_fma_f32 v33, v40, v58, v33
	s_nop 0
	v_add_f32 v13, v13, v33
	v_mov_b32_e32 v33, 0
	s_nop 0
	v_add_f32_dpp v13, v13, v13 row_ror:8 row_mask:0xf bank_mask:0xf bound_ctrl:1
	s_nop 1
	v_add_f32_dpp v13, v13, v13 row_ror:4 row_mask:0xf bank_mask:0xf bound_ctrl:1
	s_nop 1
	v_add_f32_dpp v13, v13, v13 row_ror:2 row_mask:0xf bank_mask:0xf bound_ctrl:1
	s_nop 1
	v_mov_b32_dpp v33, v13 row_ror:1 row_mask:0xf bank_mask:0xf
	s_and_saveexec_b64 s[18:19], s[4:5]
	s_cbranch_execz .LBB0_812
	s_lshl_b64 s[16:17], s[16:17], 12
	s_add_u32 s16, s22, s16
	s_addc_u32 s17, s23, s17
	s_lshl_b32 s31, s28, 2
	s_add_u32 s16, s16, s31
	s_addc_u32 s17, s17, 0
	v_add_f32_e32 v13, v13, v33
	global_store_dword v29, v13, s[16:17]
.LBB0_812:
	s_or_b64 exec, exec, s[18:19]
	s_waitcnt vmcnt(9)
	v_lshlrev_b32_e32 v33, 16, v9
	v_lshlrev_b32_e32 v34, 16, v11
	v_mul_f32 v33, v14, v33
	v_lshlrev_b32_e32 v35, 16, v5
	v_fma_f32 v33, v15, v34, v33
	v_mul_f32 v34, v41, v35
	v_lshlrev_b32_e32 v36, 16, v7
	v_fma_f32 v34, v42, v36, v34
	v_lshlrev_b32_e32 v13, 16, v8
	v_add_f32 v33, v33, v34
	v_and_b32_e32 v8, 0xffff0000, v8
	s_waitcnt vmcnt(8)
	v_sub_f32_e32 v12, v12, v31
	v_add_f32_dpp v33, v33, v33 row_ror:8 row_mask:0xf bank_mask:0xf bound_ctrl:1
	v_fma_f32 v12, v17, v12, v31
	v_mul_f32 v8, v12, v8
	v_lshlrev_b32_e32 v43, 16, v10
	v_add_f32_dpp v33, v33, v33 row_ror:4 row_mask:0xf bank_mask:0xf bound_ctrl:1
	v_and_b32_e32 v10, 0xffff0000, v10
	v_and_b32_e32 v9, 0xffff0000, v9
	v_add_f32_dpp v33, v33, v33 row_ror:2 row_mask:0xf bank_mask:0xf bound_ctrl:1
	v_and_b32_e32 v11, 0xffff0000, v11
	v_lshlrev_b32_e32 v44, 16, v4
	v_add_f32_dpp v36, v33, v33 row_ror:1 row_mask:0xf bank_mask:0xf bound_ctrl:1
	v_fma_f32 v8, v36, v9, v8
	v_and_b32_e32 v4, 0xffff0000, v4
	v_fma_f32 v33, v14, v0, v8
	v_mul_f32 v0, v12, v10
	v_and_b32_e32 v5, 0xffff0000, v5
	v_fma_f32 v0, v36, v11, v0
	v_lshlrev_b32_e32 v45, 16, v6
	v_fma_f32 v34, v15, v1, v0
	v_mul_f32 v0, v12, v4
	v_and_b32_e32 v6, 0xffff0000, v6
	v_fma_f32 v0, v36, v5, v0
	v_and_b32_e32 v7, 0xffff0000, v7
	v_fma_f32 v35, v41, v2, v0
	v_mul_f32 v0, v12, v6
	s_nop 0
	v_fma_f32 v0, v36, v7, v0
	v_mul_f32 v1, v35, v44
	s_nop 0
	v_fma_f32 v36, v42, v3, v0
	v_mul_f32 v0, v33, v13
	s_nop 0
	v_fma_f32 v0, v34, v43, v0
	v_fma_f32 v1, v36, v45, v1
	s_nop 0
	v_add_f32 v0, v0, v1
	v_mov_b32_e32 v1, 0
	s_nop 0
	v_add_f32_dpp v0, v0, v0 row_ror:8 row_mask:0xf bank_mask:0xf bound_ctrl:1
	s_nop 1
	v_add_f32_dpp v0, v0, v0 row_ror:4 row_mask:0xf bank_mask:0xf bound_ctrl:1
	s_nop 1
	v_add_f32_dpp v0, v0, v0 row_ror:2 row_mask:0xf bank_mask:0xf bound_ctrl:1
	s_nop 1
	v_mov_b32_dpp v1, v0 row_ror:1 row_mask:0xf bank_mask:0xf
	s_and_saveexec_b64 s[16:17], s[12:13]
	s_cbranch_execz .LBB0_814
	s_lshl_b64 s[14:15], s[14:15], 12
	s_add_u32 s14, s22, s14
	s_addc_u32 s15, s23, s15
	s_lshl_b32 s18, s27, 2
	s_add_u32 s14, s14, s18
	s_addc_u32 s15, s15, 0
	v_add_f32_e32 v0, v0, v1
	global_store_dword v30, v0, s[14:15]
.LBB0_814:
	s_or_b64 exec, exec, s[16:17]
	s_add_i32 s16, s29, 0x2043
	s_ashr_i32 s17, s16, 31
	s_lshl_b64 s[14:15], s[16:17], 10
	v_mov_b32_e32 v0, s28
	v_or3_b32 v0, s14, v0, v16
	s_mul_i32 s14, s16, 0x3480
	v_or3_b32 v1, s15, 0, 0
	s_mul_hi_i32 s15, s16, 0x3480
	s_add_u32 s14, s20, s14
	v_lshl_add_u64 v[2:3], v[0:1], 3, s[8:9]
	s_addc_u32 s15, s21, s15
	s_waitcnt vmcnt(0)
	v_mov_b64_e32 v[4:5], v[210:211]
	v_mov_b64_e32 v[6:7], v[212:213]
	v_mov_b64_e32 v[42:43], v[214:215]
	v_mov_b64_e32 v[44:45], v[216:217]
	v_mov_b32_e32 v41, v234
	v_lshl_add_u64 v[0:1], v[0:1], 2, s[6:7]
	v_mov_b64_e32 v[46:47], v[218:219]
	v_mov_b64_e32 v[48:49], v[220:221]
	s_add_i32 s14, s30, 0x2043
	s_ashr_i32 s15, s14, 31
	v_mov_b32_e32 v2, s27
	s_lshl_b64 s[18:19], s[14:15], 10
	s_mul_i32 s30, s14, 0x3480
	v_or3_b32 v1, s19, 0, 0
	v_or3_b32 v0, s18, v2, v16
	s_mul_hi_i32 s29, s14, 0x3480
	s_add_u32 s18, s20, s30
	v_lshl_add_u64 v[2:3], v[0:1], 2, s[6:7]
	v_lshl_add_u64 v[12:13], v[0:1], 3, s[8:9]
	s_addc_u32 s19, s21, s29
	v_mov_b64_e32 v[8:9], v[226:227]
	v_mov_b64_e32 v[10:11], v[228:229]
	s_nop 0
	v_mov_b64_e32 v[0:1], v[230:231]
	v_mov_b64_e32 v[2:3], v[232:233]
	s_nop 0
	v_mov_b64_e32 v[12:13], v[222:223]
	v_mov_b64_e32 v[14:15], v[224:225]
	s_nop 0
	v_mov_b32_e32 v27, v235
	s_waitcnt vmcnt(7)
	v_lshlrev_b32_e32 v53, 16, v5
	v_lshlrev_b32_e32 v54, 16, v7
	s_waitcnt vmcnt(5)
	v_sub_f32_e32 v32, v32, v41
	v_fmac_f32_e32 v41, v26, v32
	v_mul_f32 v26, v37, v53
	v_lshlrev_b32_e32 v55, 16, v43
	v_mul_f32 v32, v39, v55
	v_fma_f32 v26, v38, v54, v26
	v_lshlrev_b32_e32 v56, 16, v45
	v_fma_f32 v32, v40, v56, v32
	v_lshlrev_b32_e32 v28, 16, v4
	v_add_f32 v26, v26, v32
	v_and_b32_e32 v4, 0xffff0000, v4
	v_lshlrev_b32_e32 v50, 16, v6
	v_add_f32_dpp v26, v26, v26 row_ror:8 row_mask:0xf bank_mask:0xf bound_ctrl:1
	v_and_b32_e32 v6, 0xffff0000, v6
	v_mul_f32 v4, v41, v4
	v_lshlrev_b32_e32 v51, 16, v42
	v_add_f32_dpp v26, v26, v26 row_ror:4 row_mask:0xf bank_mask:0xf bound_ctrl:1
	v_and_b32_e32 v42, 0xffff0000, v42
	v_and_b32_e32 v5, 0xffff0000, v5
	v_add_f32_dpp v26, v26, v26 row_ror:2 row_mask:0xf bank_mask:0xf bound_ctrl:1
	v_and_b32_e32 v7, 0xffff0000, v7
	v_mul_f32 v6, v41, v6
	v_lshlrev_b32_e32 v52, 16, v44
	v_add_f32_dpp v26, v26, v26 row_ror:1 row_mask:0xf bank_mask:0xf bound_ctrl:1
	v_fma_f32 v4, v26, v5, v4
	v_and_b32_e32 v44, 0xffff0000, v44
	v_and_b32_e32 v43, 0xffff0000, v43
	v_and_b32_e32 v45, 0xffff0000, v45
	v_mul_f32 v42, v41, v42
	v_mul_f32 v41, v41, v44
	v_fma_f32 v5, v26, v7, v6
	s_waitcnt vmcnt(4)
	v_fma_f32 v4, v37, v46, v4
	v_fma_f32 v6, v26, v43, v42
	v_fma_f32 v7, v26, v45, v41
	s_nop 0
	v_mul_f32 v26, v4, v28
	v_fma_f32 v5, v38, v47, v5
	v_fma_f32 v6, v39, v48, v6
	s_nop 0
	v_fma_f32 v26, v5, v50, v26
	v_fma_f32 v7, v40, v49, v7
	v_mul_f32 v28, v6, v51
	s_nop 0
	v_fma_f32 v28, v7, v52, v28
	s_nop 0
	v_add_f32 v26, v26, v28
	v_mov_b32_e32 v28, 0
	s_nop 0
	v_add_f32_dpp v26, v26, v26 row_ror:8 row_mask:0xf bank_mask:0xf bound_ctrl:1
	s_nop 1
	v_add_f32_dpp v26, v26, v26 row_ror:4 row_mask:0xf bank_mask:0xf bound_ctrl:1
	s_nop 1
	v_add_f32_dpp v26, v26, v26 row_ror:2 row_mask:0xf bank_mask:0xf bound_ctrl:1
	s_nop 1
	v_mov_b32_dpp v28, v26 row_ror:1 row_mask:0xf bank_mask:0xf
	s_and_saveexec_b64 s[18:19], s[4:5]
	s_cbranch_execz .LBB0_816
	s_lshl_b64 s[16:17], s[16:17], 12
	s_add_u32 s16, s22, s16
	s_addc_u32 s17, s23, s17
	s_lshl_b32 s28, s28, 2
	s_add_u32 s16, s16, s28
	s_addc_u32 s17, s17, 0
	v_add_f32_e32 v26, v26, v28
	global_store_dword v29, v26, s[16:17]
